# GLA summary: per-wave 8-tile kv MFMA loop unrolled by hand (LDS reads in flight, MFMAs back to back)
# speedup vs baseline: 1.0043x; 1.0043x over previous
; #define LBAR do { asm volatile("s_waitcnt lgkmcnt(0)" ::: "memory"); __builtin_amdgcn_s_barrier(); } while (0)
; __device__ __forceinline__ void gla_summ_unit(const P& p, int unit, const SummRaw& raw) {
;     ...
;   int fr = lane & 15, fq = lane >> 4;
; #pragma unroll 1
;   for (int tI = 0; tI < 8; ++tI) {
;     int tile = wid * 8 + tI;
;     int dir = tile >> 5, dkt = (tile >> 3) & 3, dvt = tile & 7;
;     const u16* Asrc = (dir ? kdbT : kdfT) + (dkt * 16 + fr) * LP + fq * 8;
;     const u16* Bsrc = vT + (dvt * 16 + fr) * LP + fq * 8;
;     f32x4 d = {0.f, 0.f, 0.f, 0.f};
; #pragma unroll
;     for (int ks = 0; ks < 2; ++ks) {
;       bf16x8 a = *(const bf16x8*)(Asrc + ks * 32);
;       bf16x8 b = *(const bf16x8*)(Bsrc + ks * 32);
;       d = __builtin_amdgcn_mfma_f32_16x16x32_bf16(a, b, d, 0, 0, 0);
;     }
;     uint2 w; w.x = pack2(d[0], d[1]); w.y = pack2(d[2], d[3]);
;     *(uint2*)(kvout + (size_t)(unit * 2 + dir) * 8192 + (dvt * 16 + fr) * 64 + dkt * 16 + fq * 4) = w;
;   }
;   LBAR;
; }
; __device__ void phase_gla_summ(const P& p) {
;   int tid = opaque_tid(p);
;   int u = blockIdx.x;
;   if (u >= 4096) return;
;   SummRaw cur = gla_summ_load(p, u, tid);
;   for (; u < 4096; u += gridDim.x) {
;     int un = u + gridDim.x;
;     SummRaw nxt = gla_summ_load(p, un < 4096 ? un : u, tid);
;     gla_summ_unit(p, u, cur);
;     cur = nxt;
.LBB0_226:
	s_or_b64 exec, exec, s[26:27]
	v_and_b32_e32 v31, 15, v51
	v_cmp_gt_u32_e32 vcc, s40, v43
	v_lshlrev_b32_e32 v9, 4, v45
	v_ashrrev_i32_e32 v44, 8, v43
	v_cndmask_b32_e32 v8, v49, v50, vcc
	v_and_or_b32 v9, v9, 48, v31
	s_ashr_i32 s21, s20, 31
	v_add_u32_e32 v8, 16, v8
	v_mul_u32_u24_e32 v9, 0x90, v9
	v_and_b32_e32 v28, 48, v28
	v_mul_u32_u24_e32 v29, 0x90, v31
	v_ashrrev_i32_e32 v45, 31, v44
	v_add3_u32 v12, v8, v9, v28
	v_add3_u32 v30, v29, v28, 16
	v_lshl_add_u64 v[28:29], v[44:45], 0, s[20:21]
	s_waitcnt lgkmcnt(0)
	s_barrier
	ds_read_b128 v[8:11], v12
	ds_read_b128 v[12:15], v12 offset:64
	v_lshlrev_b64 v[28:29], 14, v[28:29]
	v_lshl_or_b32 v28, v31, 7, v28
	v_lshrrev_b32_e32 v31, 1, v43
	v_and_b32_e32 v34, 48, v51
	v_and_b32_e32 v31, 0x60, v31
	v_lshrrev_b32_e32 v34, 1, v34
	v_or3_b32 v28, v28, v31, v34
	v_lshl_add_u64 v[28:29], s[10:11], 0, v[28:29]
	v_add_u32_e32 v34, 0x11200, v30
	ds_read_b128 v[80:83], v34
	ds_read_b128 v[84:87], v34 offset:64
	ds_read_b128 v[88:91], v34 offset:2304
	ds_read_b128 v[92:95], v34 offset:2368
	ds_read_b128 v[96:99], v34 offset:4608
	ds_read_b128 v[100:103], v34 offset:4672
	ds_read_b128 v[104:107], v34 offset:6912
	ds_read_b128 v[108:111], v34 offset:6976
	ds_read_b128 v[112:115], v34 offset:9216
	ds_read_b128 v[116:119], v34 offset:9280
	ds_read_b128 v[120:123], v34 offset:11520
	ds_read_b128 v[124:127], v34 offset:11584
	s_waitcnt lgkmcnt(10)
	v_mfma_f32_16x16x32_bf16 v[80:83], v[8:11], v[80:83], 0
	v_mfma_f32_16x16x32_bf16 v[80:83], v[12:15], v[84:87], v[80:83]
	s_waitcnt lgkmcnt(8)
	v_mfma_f32_16x16x32_bf16 v[88:91], v[8:11], v[88:91], 0
	v_mfma_f32_16x16x32_bf16 v[88:91], v[12:15], v[92:95], v[88:91]
	ds_read_b128 v[128:131], v34 offset:13824
	ds_read_b128 v[132:135], v34 offset:13888
	s_waitcnt lgkmcnt(8)
	v_mfma_f32_16x16x32_bf16 v[96:99], v[8:11], v[96:99], 0
	v_mfma_f32_16x16x32_bf16 v[96:99], v[12:15], v[100:103], v[96:99]
	ds_read_b128 v[136:139], v34 offset:16128
	ds_read_b128 v[140:143], v34 offset:16192
	s_waitcnt lgkmcnt(8)
	v_mfma_f32_16x16x32_bf16 v[104:107], v[8:11], v[104:107], 0
	v_mfma_f32_16x16x32_bf16 v[104:107], v[12:15], v[108:111], v[104:107]
	s_waitcnt lgkmcnt(6)
	v_mfma_f32_16x16x32_bf16 v[112:115], v[8:11], v[112:115], 0
	v_mfma_f32_16x16x32_bf16 v[112:115], v[12:15], v[116:119], v[112:115]
	s_waitcnt lgkmcnt(4)
	v_mfma_f32_16x16x32_bf16 v[120:123], v[8:11], v[120:123], 0
	v_mfma_f32_16x16x32_bf16 v[120:123], v[12:15], v[124:127], v[120:123]
	s_waitcnt lgkmcnt(2)
	v_mfma_f32_16x16x32_bf16 v[128:131], v[8:11], v[128:131], 0
	v_mfma_f32_16x16x32_bf16 v[128:131], v[12:15], v[132:135], v[128:131]
	s_waitcnt lgkmcnt(0)
	v_mfma_f32_16x16x32_bf16 v[136:139], v[8:11], v[136:139], 0
	v_mfma_f32_16x16x32_bf16 v[136:139], v[12:15], v[140:143], v[136:139]
	v_cvt_pk_bf16_f32 v80, v80, v81
	v_cvt_pk_bf16_f32 v81, v82, v83
	global_store_dwordx2 v[28:29], v[80:81], off offset:-4
	v_lshl_add_u64 v[28:29], v[28:29], 0, s[22:23]
	v_cvt_pk_bf16_f32 v88, v88, v89
	v_cvt_pk_bf16_f32 v89, v90, v91
	global_store_dwordx2 v[28:29], v[88:89], off offset:-4
	v_lshl_add_u64 v[28:29], v[28:29], 0, s[22:23]
	v_cvt_pk_bf16_f32 v96, v96, v97
	v_cvt_pk_bf16_f32 v97, v98, v99
	global_store_dwordx2 v[28:29], v[96:97], off offset:-4
	v_lshl_add_u64 v[28:29], v[28:29], 0, s[22:23]
	v_cvt_pk_bf16_f32 v104, v104, v105
	v_cvt_pk_bf16_f32 v105, v106, v107
	global_store_dwordx2 v[28:29], v[104:105], off offset:-4
	v_lshl_add_u64 v[28:29], v[28:29], 0, s[22:23]
	v_cvt_pk_bf16_f32 v112, v112, v113
	v_cvt_pk_bf16_f32 v113, v114, v115
	global_store_dwordx2 v[28:29], v[112:113], off offset:-4
	v_lshl_add_u64 v[28:29], v[28:29], 0, s[22:23]
	v_cvt_pk_bf16_f32 v120, v120, v121
	v_cvt_pk_bf16_f32 v121, v122, v123
	global_store_dwordx2 v[28:29], v[120:121], off offset:-4
	v_lshl_add_u64 v[28:29], v[28:29], 0, s[22:23]
	v_cvt_pk_bf16_f32 v128, v128, v129
	v_cvt_pk_bf16_f32 v129, v130, v131
	global_store_dwordx2 v[28:29], v[128:129], off offset:-4
	v_lshl_add_u64 v[28:29], v[28:29], 0, s[22:23]
	v_cvt_pk_bf16_f32 v136, v136, v137
	v_cvt_pk_bf16_f32 v137, v138, v139
	global_store_dwordx2 v[28:29], v[136:137], off offset:-4
	v_lshl_add_u64 v[28:29], v[28:29], 0, s[22:23]
	s_waitcnt lgkmcnt(0)
	s_add_i32 s20, s20, s3
	s_andn2_b64 vcc, exec, s[24:25]
	s_mov_b32 s21, s46
	s_waitcnt vmcnt(3)
	v_mov_b64_e32 v[12:13], v[20:21]
	v_mov_b64_e32 v[14:15], v[22:23]
	s_waitcnt vmcnt(1)
	v_mov_b64_e32 v[8:9], v[24:25]
	v_mov_b64_e32 v[10:11], v[26:27]
	v_mov_b64_e32 v[28:29], v[16:17]
	v_mov_b64_e32 v[30:31], v[18:19]
	s_barrier
	s_cbranch_vccnz .LBB0_224
